# in-proj and FFN-up epilogues: the wait that guarantees the next unit's prefetch DMAs moved from before the first store to a counted wait after the last store
# speedup vs baseline: 1.0035x; 1.0035x over previous
.LBB0_416:
	v_cvt_pk_bf16_f32 v2, v12, v13
	v_cvt_pk_bf16_f32 v3, v14, v15
	v_cvt_pk_bf16_f32 v4, v26, v27
	v_cvt_pk_bf16_f32 v5, v16, v17
	s_andn2_b64 vcc, exec, s[24:25]
	s_mov_b64 s[10:11], -1
	global_store_dwordx4 v[10:11], v[2:5], off offset:256
	s_waitcnt vmcnt(8)
	s_cbranch_vccnz .LBB0_289
	s_andn2_b64 vcc, exec, s[4:5]
	s_cbranch_vccnz .LBB0_288
	s_barrier
	s_branch .LBB0_288

.LBB0_1217:
	v_lshl_add_u32 v198, s29, 8, v205
	v_or_b32_e32 v192, 16, v198
	v_ashrrev_i32_e32 v199, 31, v198
	v_ashrrev_i32_e32 v193, 31, v192
	v_or_b32_e32 v190, 32, v198
	v_lshl_or_b32 v194, s28, 7, v209
	v_lshlrev_b32_e32 v254, 2, v205
	v_add_u32_e32 v254, 0x22f80, v254
	v_lshlrev_b32_e32 v255, 2, v209
	v_add_u32_e32 v255, 0x23380, v255
	v_ashrrev_i32_e32 v191, 31, v190
	v_or_b32_e32 v188, 48, v198
	v_ashrrev_i32_e32 v195, 31, v194
	ds_read_b32 v220, v254
	ds_read_b32 v219, v254 offset:64
	ds_read_b32 v216, v254 offset:512
	ds_read_b32 v215, v254 offset:576
	ds_read_b32 v214, v254 offset:640
	ds_read_b32 v211, v254 offset:704
	v_ashrrev_i32_e32 v189, 31, v188
	ds_read_b32 v218, v254 offset:128
	ds_read_b32 v217, v254 offset:192
	ds_read_b32 v252, v255 offset:16
	s_mov_b32 s28, 0x3c010204
	ds_read_b32 v250, v255
	v_add_u32_e32 v186, 0x80, v198
	ds_read_b32 v253, v255 offset:528
	v_ashrrev_i32_e32 v187, 31, v186
	ds_read_b32 v251, v255 offset:512
	v_add_u32_e32 v184, 0x90, v198
	v_ashrrev_i32_e32 v185, 31, v184
	v_add_u32_e32 v182, 0xa0, v198
	v_ashrrev_i32_e32 v183, 31, v182
	v_add_u32_e32 v180, 0xb0, v198
	v_ashrrev_i32_e32 v181, 31, v180
	v_lshlrev_b32_e32 v226, 5, v205
	v_add_u32_e32 v226, 0x20f80, v226
	v_cvt_f32_i32_e32 v127, v127
	v_cvt_f32_i32_e32 v126, v126
	v_cvt_f32_i32_e32 v123, v123
	v_cvt_f32_i32_e32 v122, v122
	v_cvt_f32_i32_e32 v119, v119
	v_cvt_f32_i32_e32 v118, v118
	v_cvt_f32_i32_e32 v115, v115
	v_cvt_f32_i32_e32 v114, v114
	v_cvt_f32_i32_e32 v129, v129
	v_cvt_f32_i32_e32 v128, v128
	v_cvt_f32_i32_e32 v117, v117
	v_pk_mul_f32 v[114:115], v[114:115], v[118:119]
	v_cvt_f32_i32_e32 v116, v116
	s_movk_i32 s23, 0x2c00
	v_cvt_f32_i32_e32 v111, v111
	v_cvt_f32_i32_e32 v110, v110
	v_cvt_f32_i32_e32 v107, v107
	v_cvt_f32_i32_e32 v106, v106
	v_cvt_f32_i32_e32 v103, v103
	v_cvt_f32_i32_e32 v102, v102
	v_cvt_f32_i32_e32 v99, v99
	v_pk_mul_f32 v[106:107], v[106:107], v[110:111]
	v_cvt_f32_i32_e32 v98, v98
	v_cvt_f32_i32_e32 v109, v109
	v_cvt_f32_i32_e32 v108, v108
	v_cvt_f32_i32_e32 v101, v101
	v_pk_mul_f32 v[98:99], v[98:99], v[102:103]
	v_cvt_f32_i32_e32 v100, v100
	v_cvt_f32_i32_e32 v95, v95
	v_cvt_f32_i32_e32 v94, v94
	v_cvt_f32_i32_e32 v91, v91
	v_cvt_f32_i32_e32 v90, v90
	v_cvt_f32_i32_e32 v87, v87
	v_cvt_f32_i32_e32 v86, v86
	v_cvt_f32_i32_e32 v83, v83
	v_pk_mul_f32 v[90:91], v[90:91], v[94:95]
	v_cvt_f32_i32_e32 v82, v82
	v_cvt_f32_i32_e32 v93, v93
	v_cvt_f32_i32_e32 v92, v92
	v_cvt_f32_i32_e32 v85, v85
	v_pk_mul_f32 v[82:83], v[82:83], v[86:87]
	v_cvt_f32_i32_e32 v84, v84
	v_cvt_f32_i32_e32 v79, v79
	v_cvt_f32_i32_e32 v78, v78
	v_cvt_f32_i32_e32 v75, v75
	v_cvt_f32_i32_e32 v74, v74
	v_cvt_f32_i32_e32 v71, v71
	v_cvt_f32_i32_e32 v70, v70
	v_cvt_f32_i32_e32 v67, v67
	v_pk_mul_f32 v[74:75], v[74:75], v[78:79]
	v_cvt_f32_i32_e32 v66, v66
	v_cvt_f32_i32_e32 v77, v77
	v_cvt_f32_i32_e32 v76, v76
	v_cvt_f32_i32_e32 v69, v69
	v_pk_mul_f32 v[66:67], v[66:67], v[70:71]
	v_cvt_f32_i32_e32 v68, v68
	v_cvt_f32_i32_e32 v63, v63
	v_cvt_f32_i32_e32 v62, v62
	v_cvt_f32_i32_e32 v59, v59
	v_cvt_f32_i32_e32 v58, v58
	v_cvt_f32_i32_e32 v55, v55
	v_cvt_f32_i32_e32 v54, v54
	v_cvt_f32_i32_e32 v51, v51
	v_pk_mul_f32 v[58:59], v[58:59], v[62:63]
	v_cvt_f32_i32_e32 v50, v50
	v_cvt_f32_i32_e32 v61, v61
	v_cvt_f32_i32_e32 v60, v60
	v_pk_mul_f32 v[50:51], v[50:51], v[54:55]
	ds_read_b128 v[222:225], v226
	ds_read_b128 v[236:239], v226 offset:16
	ds_read_b128 v[150:153], v226 offset:512
	ds_read_b128 v[146:149], v226 offset:528
	ds_read_b128 v[134:137], v226 offset:1024
	ds_read_b128 v[130:133], v226 offset:1040
	ds_read_b128 v[142:145], v226 offset:1536
	ds_read_b128 v[138:141], v226 offset:1552
	ds_read_b128 v[174:177], v226 offset:4096
	ds_read_b128 v[166:169], v226 offset:4112
	ds_read_b128 v[170:173], v226 offset:4608
	ds_read_b128 v[162:165], v226 offset:4624
	ds_read_b128 v[158:161], v226 offset:5120
	ds_read_b128 v[154:157], v226 offset:5136
	ds_read_b128 v[240:243], v226 offset:5632
	ds_read_b128 v[244:247], v226 offset:5648
	v_cvt_f32_i32_e32 v53, v53
	v_cvt_f32_i32_e32 v52, v52
	v_cvt_f32_i32_e32 v47, v47
	v_cvt_f32_i32_e32 v46, v46
	v_cvt_f32_i32_e32 v43, v43
	v_cvt_f32_i32_e32 v42, v42
	v_cvt_f32_i32_e32 v39, v39
	v_cvt_f32_i32_e32 v38, v38
	v_cvt_f32_i32_e32 v35, v35
	v_pk_mul_f32 v[42:43], v[42:43], v[46:47]
	v_cvt_f32_i32_e32 v34, v34
	v_cvt_f32_i32_e32 v45, v45
	v_cvt_f32_i32_e32 v44, v44
	v_cvt_f32_i32_e32 v37, v37
	v_pk_mul_f32 v[34:35], v[34:35], v[38:39]
	v_cvt_f32_i32_e32 v36, v36
	v_cvt_f32_i32_e32 v31, v31
	v_cvt_f32_i32_e32 v30, v30
	v_cvt_f32_i32_e32 v27, v27
	v_cvt_f32_i32_e32 v26, v26
	v_cvt_f32_i32_e32 v23, v23
	v_cvt_f32_i32_e32 v22, v22
	v_cvt_f32_i32_e32 v19, v19
	v_pk_mul_f32 v[26:27], v[26:27], v[30:31]
	v_cvt_f32_i32_e32 v18, v18
	v_cvt_f32_i32_e32 v29, v29
	v_cvt_f32_i32_e32 v28, v28
	v_cvt_f32_i32_e32 v21, v21
	v_pk_mul_f32 v[18:19], v[18:19], v[22:23]
	v_cvt_f32_i32_e32 v20, v20
	v_cvt_f32_i32_e32 v15, v15
	v_cvt_f32_i32_e32 v14, v14
	v_cvt_f32_i32_e32 v11, v11
	v_cvt_f32_i32_e32 v10, v10
	v_cvt_f32_i32_e32 v7, v7
	v_cvt_f32_i32_e32 v6, v6
	v_cvt_f32_i32_e32 v3, v3
	v_pk_mul_f32 v[10:11], v[10:11], v[14:15]
	v_cvt_f32_i32_e32 v2, v2
	v_cvt_f32_i32_e32 v13, v13
	v_cvt_f32_i32_e32 v12, v12
	v_cvt_f32_i32_e32 v5, v5
	v_pk_mul_f32 v[2:3], v[2:3], v[6:7]
	v_cvt_f32_i32_e32 v4, v4
	s_mov_b64 s[42:43], -1
	s_andn2_b64 vcc, exec, s[38:39]
	s_waitcnt lgkmcnt(0)
	v_pk_mul_f32 v[196:197], v[250:251], s[28:29] op_sel_hi:[1,0]
	v_pk_mul_f32 v[200:201], v[252:253], s[28:29] op_sel_hi:[1,0]
	v_mul_f32_e32 v254, v196, v197
	v_rcp_f32_e32 v212, v254
	v_mul_f32_e32 v255, v200, v201
	v_rcp_f32_e32 v213, v255
	v_mov_b32_e32 v197, v219
	v_mov_b32_e32 v201, v220
	v_mov_b32_e32 v226, v222
	v_mov_b32_e32 v227, v236
	v_mov_b32_e32 v236, v223
	v_pk_add_f32 v[222:223], v[226:227], v[236:237]
	v_mov_b32_e32 v226, v224
	v_mov_b32_e32 v227, v238
	v_mov_b32_e32 v238, v225
	v_pk_add_f32 v[224:225], v[226:227], v[238:239]
	s_nop 0
	v_pk_add_f32 v[222:223], v[222:223], v[224:225]
	s_nop 0
	v_add_f32_e32 v181, v222, v223
	v_mov_b32_e32 v222, v150
	v_mov_b32_e32 v223, v146
	v_mov_b32_e32 v146, v151
	v_mov_b32_e32 v150, v152
	v_mov_b32_e32 v151, v148
	v_mov_b32_e32 v148, v153
	v_pk_add_f32 v[146:147], v[222:223], v[146:147]
	v_pk_add_f32 v[148:149], v[150:151], v[148:149]
	v_fmamk_f32 v181, v181, 0x3a000000, v1
	v_pk_add_f32 v[146:147], v[146:147], v[148:149]
	v_rsq_f32_e32 v207, v181
	v_add_f32_e32 v146, v146, v147
	v_fmamk_f32 v146, v146, 0x3a000000, v1
	v_rsq_f32_e32 v148, v146
	v_mov_b32_e32 v146, v134
	v_mov_b32_e32 v147, v130
	v_mov_b32_e32 v130, v135
	v_mov_b32_e32 v134, v136
	v_mov_b32_e32 v135, v132
	v_mov_b32_e32 v132, v137
	v_pk_add_f32 v[130:131], v[146:147], v[130:131]
	v_pk_add_f32 v[132:133], v[134:135], v[132:133]
	s_nop 0
	v_pk_add_f32 v[130:131], v[130:131], v[132:133]
	v_mov_b32_e32 v132, v144
	v_add_f32_e32 v130, v130, v131
	v_fmamk_f32 v130, v130, 0x3a000000, v1
	v_rsq_f32_e32 v146, v130
	v_mov_b32_e32 v130, v142
	v_mov_b32_e32 v131, v138
	v_mov_b32_e32 v138, v143
	v_mov_b32_e32 v133, v140
	v_mov_b32_e32 v140, v145
	v_pk_add_f32 v[130:131], v[130:131], v[138:139]
	v_pk_add_f32 v[132:133], v[132:133], v[140:141]
	v_pk_mul_f32 v[142:143], v[122:123], v[126:127]
	v_pk_add_f32 v[130:131], v[130:131], v[132:133]
	v_mov_b32_e32 v132, v176
	v_add_f32_e32 v130, v130, v131
	v_fmamk_f32 v130, v130, 0x3a000000, v1
	v_rsq_f32_e32 v138, v130
	v_mov_b32_e32 v130, v174
	v_mov_b32_e32 v131, v166
	v_mov_b32_e32 v166, v175
	v_mov_b32_e32 v133, v168
	v_mov_b32_e32 v168, v177
	v_pk_add_f32 v[130:131], v[130:131], v[166:167]
	v_pk_add_f32 v[132:133], v[132:133], v[168:169]
	s_nop 0
	v_pk_add_f32 v[130:131], v[130:131], v[132:133]
	v_mov_b32_e32 v132, v172
	v_add_f32_e32 v130, v130, v131
	v_fmamk_f32 v130, v130, 0x3a000000, v1
	v_rsq_f32_e32 v137, v130
	v_mov_b32_e32 v130, v170
	v_mov_b32_e32 v131, v162
	v_mov_b32_e32 v162, v171
	v_mov_b32_e32 v133, v164
	v_mov_b32_e32 v164, v173
	v_pk_add_f32 v[130:131], v[130:131], v[162:163]
	v_pk_add_f32 v[132:133], v[132:133], v[164:165]
	s_nop 0
	v_pk_add_f32 v[130:131], v[130:131], v[132:133]
	v_mov_b32_e32 v132, v160
	v_add_f32_e32 v130, v130, v131
	v_fmamk_f32 v130, v130, 0x3a000000, v1
	v_rsq_f32_e32 v136, v130
	v_mov_b32_e32 v130, v158
	v_mov_b32_e32 v131, v154
	v_mov_b32_e32 v154, v159
	v_mov_b32_e32 v133, v156
	v_mov_b32_e32 v156, v161
	v_pk_add_f32 v[130:131], v[130:131], v[154:155]
	v_pk_add_f32 v[132:133], v[132:133], v[156:157]
	s_nop 0
	v_pk_add_f32 v[130:131], v[130:131], v[132:133]
	v_mov_b32_e32 v132, v242
	v_add_f32_e32 v130, v130, v131
	v_fmamk_f32 v130, v130, 0x3a000000, v1
	v_rsq_f32_e32 v135, v130
	v_mov_b32_e32 v130, v240
	v_mov_b32_e32 v131, v244
	v_mov_b32_e32 v244, v241
	v_mov_b32_e32 v133, v246
	v_mov_b32_e32 v246, v243
	v_pk_add_f32 v[130:131], v[130:131], v[244:245]
	v_pk_add_f32 v[132:133], v[132:133], v[246:247]
	s_nop 0
	v_pk_add_f32 v[130:131], v[130:131], v[132:133]
	v_pk_mul_f32 v[132:133], v[200:201], v[206:207]
	v_mov_b32_e32 v207, v148
	v_mul_f32_e32 v139, v133, v133
	v_mul_f32_e32 v145, v132, v133
	v_rcp_f32_e32 v139, v139
	v_mul_f32_e32 v122, v145, v118
	v_mul_f32_e32 v123, v145, v119
	v_exp_f32_e32 v122, v122
	v_exp_f32_e32 v123, v123
	v_mul_f32_e32 v144, v212, v139
	v_mul_f32_e32 v139, v213, v139
	v_fma_f32 v122, v122, v139, v139
	v_fma_f32 v118, v123, v139, v139
	v_rcp_f32_e32 v122, v122
	v_rcp_f32_e32 v123, v118
	v_add_f32_e32 v130, v130, v131
	v_fmamk_f32 v130, v130, 0x3a000000, v1
	v_rsq_f32_e32 v134, v130
	v_pk_mul_f32 v[118:119], v[114:115], v[122:123]
	v_cvt_f32_i32_e32 v115, v125
	v_cvt_f32_i32_e32 v114, v124
	v_mov_b64_e32 v[130:131], s[6:7]
	v_mad_i64_i32 v[140:141], s[28:29], v198, s23, v[130:131]
	v_pk_mul_f32 v[124:125], v[114:115], v[128:129]
	v_cvt_f32_i32_e32 v115, v121
	v_cvt_f32_i32_e32 v114, v120
	v_cvt_pk_bf16_f32 v122, v118, v119
	v_mad_i64_i32 v[118:119], s[28:29], v192, s23, v[130:131]
	v_mul_f32_e32 v120, v145, v114
	v_mul_f32_e32 v121, v145, v115
	v_exp_f32_e32 v120, v120
	v_exp_f32_e32 v121, v121
	v_pk_mul_f32 v[114:115], v[116:117], v[114:115]
	v_fma_f32 v120, v120, v139, v139
	v_fmac_f32_e32 v139, v121, v139
	v_rcp_f32_e32 v120, v120
	v_rcp_f32_e32 v121, v139
	s_nop 0
	v_pk_mul_f32 v[116:117], v[114:115], v[120:121]
	s_nop 0
	v_cvt_pk_bf16_f32 v123, v116, v117
	v_pk_mul_f32 v[116:117], v[196:197], v[206:207]
	v_lshlrev_b64 v[114:115], 1, v[194:195]
	v_mul_f32_e32 v133, v116, v133
	v_mul_f32_e32 v120, v133, v126
	v_mul_f32_e32 v121, v133, v127
	v_mul_f32_e32 v126, v133, v128
	v_mul_f32_e32 v127, v133, v129
	v_exp_f32_e32 v120, v120
	v_exp_f32_e32 v121, v121
	v_exp_f32_e32 v126, v126
	v_exp_f32_e32 v127, v127
	v_fma_f32 v120, v120, v144, v144
	v_fma_f32 v121, v121, v144, v144
	v_fma_f32 v126, v126, v144, v144
	v_fmac_f32_e32 v144, v127, v144
	v_rcp_f32_e32 v120, v120
	v_rcp_f32_e32 v121, v121
	v_rcp_f32_e32 v126, v126
	v_rcp_f32_e32 v127, v144
	v_lshl_add_u64 v[140:141], v[140:141], 0, v[114:115]
	v_pk_mul_f32 v[120:121], v[142:143], v[120:121]
	v_pk_mul_f32 v[124:125], v[124:125], v[126:127]
	v_cvt_pk_bf16_f32 v120, v120, v121
	v_cvt_pk_bf16_f32 v121, v124, v125
	global_store_dwordx4 v[140:141], v[120:123], off
	v_mul_f32_e32 v124, v116, v117
	s_nop 0
	v_mul_f32_e32 v120, v117, v117
	v_rcp_f32_e32 v120, v120
	v_mul_f32_e32 v121, v124, v111
	v_exp_f32_e32 v121, v121
	v_mul_f32_e32 v117, v132, v117
	v_mul_f32_e32 v122, v212, v120
	v_mul_f32_e32 v123, v213, v120
	v_mul_f32_e32 v120, v124, v110
	v_fma_f32 v110, v121, v122, v122
	v_rcp_f32_e32 v121, v110
	v_mul_f32_e32 v110, v117, v102
	v_mul_f32_e32 v111, v117, v103
	v_exp_f32_e32 v110, v110
	v_exp_f32_e32 v111, v111
	v_exp_f32_e32 v120, v120
	v_fma_f32 v110, v110, v123, v123
	v_fma_f32 v102, v111, v123, v123
	v_rcp_f32_e32 v110, v110
	v_rcp_f32_e32 v111, v102
	v_fma_f32 v120, v120, v122, v122
	v_rcp_f32_e32 v120, v120
	v_pk_mul_f32 v[102:103], v[98:99], v[110:111]
	v_cvt_f32_i32_e32 v99, v113
	v_cvt_f32_i32_e32 v98, v112
	v_pk_mul_f32 v[106:107], v[106:107], v[120:121]
	v_mul_f32_e32 v111, v124, v99
	v_mul_f32_e32 v110, v124, v98
	v_exp_f32_e32 v110, v110
	v_exp_f32_e32 v111, v111
	v_pk_mul_f32 v[98:99], v[108:109], v[98:99]
	v_fma_f32 v110, v110, v122, v122
	v_fmac_f32_e32 v122, v111, v122
	v_rcp_f32_e32 v110, v110
	v_rcp_f32_e32 v111, v122
	s_nop 0
	v_pk_mul_f32 v[108:109], v[98:99], v[110:111]
	v_cvt_f32_i32_e32 v99, v105
	v_cvt_f32_i32_e32 v98, v104
	v_lshl_add_u64 v[110:111], v[118:119], 0, v[114:115]
	v_mul_f32_e32 v105, v117, v99
	v_mul_f32_e32 v104, v117, v98
	v_exp_f32_e32 v104, v104
	v_exp_f32_e32 v105, v105
	v_pk_mul_f32 v[98:99], v[100:101], v[98:99]
	v_cvt_pk_bf16_f32 v100, v102, v103
	v_fma_f32 v104, v104, v123, v123
	v_fmac_f32_e32 v123, v105, v123
	v_rcp_f32_e32 v104, v104
	v_rcp_f32_e32 v105, v123
	s_nop 0
	v_pk_mul_f32 v[104:105], v[98:99], v[104:105]
	v_cvt_pk_bf16_f32 v98, v106, v107
	v_cvt_pk_bf16_f32 v99, v108, v109
	v_cvt_pk_bf16_f32 v101, v104, v105
	global_store_dwordx4 v[110:111], v[98:101], off
	s_nop 1
	v_mul_f32_e32 v100, v218, v146
	v_mul_f32_e32 v101, v100, v100
	v_rcp_f32_e32 v101, v101
	v_mul_f32_e32 v102, v116, v100
	v_mul_f32_e32 v103, v132, v100
	v_mul_f32_e32 v100, v102, v94
	v_mul_f32_e32 v104, v212, v101
	v_mul_f32_e32 v105, v213, v101
	v_mul_f32_e32 v101, v102, v95
	v_exp_f32_e32 v101, v101
	v_mul_f32_e32 v95, v103, v87
	v_exp_f32_e32 v95, v95
	v_exp_f32_e32 v100, v100
	v_fma_f32 v94, v101, v104, v104
	v_rcp_f32_e32 v101, v94
	v_mul_f32_e32 v94, v103, v86
	v_exp_f32_e32 v94, v94
	v_fma_f32 v86, v95, v105, v105
	v_rcp_f32_e32 v95, v86
	v_fma_f32 v100, v100, v104, v104
	v_fma_f32 v94, v94, v105, v105
	v_rcp_f32_e32 v94, v94
	v_rcp_f32_e32 v100, v100
	v_mad_i64_i32 v[98:99], s[28:29], v190, s23, v[130:131]
	v_pk_mul_f32 v[86:87], v[82:83], v[94:95]
	v_cvt_f32_i32_e32 v83, v97
	v_cvt_f32_i32_e32 v82, v96
	v_pk_mul_f32 v[90:91], v[90:91], v[100:101]
	v_mul_f32_e32 v95, v102, v83
	v_mul_f32_e32 v94, v102, v82
	v_exp_f32_e32 v94, v94
	v_exp_f32_e32 v95, v95
	v_pk_mul_f32 v[82:83], v[92:93], v[82:83]
	v_fma_f32 v94, v94, v104, v104
	v_fmac_f32_e32 v104, v95, v104
	v_rcp_f32_e32 v94, v94
	v_rcp_f32_e32 v95, v104
	s_nop 0
	v_pk_mul_f32 v[92:93], v[82:83], v[94:95]
	v_cvt_f32_i32_e32 v83, v89
	v_cvt_f32_i32_e32 v82, v88
	v_lshl_add_u64 v[94:95], v[98:99], 0, v[114:115]
	v_mul_f32_e32 v89, v103, v83
	v_mul_f32_e32 v88, v103, v82
	v_exp_f32_e32 v88, v88
	v_exp_f32_e32 v89, v89
	v_pk_mul_f32 v[82:83], v[84:85], v[82:83]
	v_cvt_pk_bf16_f32 v84, v86, v87
	v_fma_f32 v88, v88, v105, v105
	v_fmac_f32_e32 v105, v89, v105
	v_rcp_f32_e32 v88, v88
	v_rcp_f32_e32 v89, v105
	s_nop 0
	v_pk_mul_f32 v[88:89], v[82:83], v[88:89]
	v_cvt_pk_bf16_f32 v82, v90, v91
	v_cvt_pk_bf16_f32 v83, v92, v93
	v_cvt_pk_bf16_f32 v85, v88, v89
	global_store_dwordx4 v[94:95], v[82:85], off
	s_nop 1
	v_mul_f32_e32 v84, v217, v138
	v_mul_f32_e32 v85, v84, v84
	v_rcp_f32_e32 v85, v85
	v_mul_f32_e32 v86, v116, v84
	v_mul_f32_e32 v87, v132, v84
	v_mul_f32_e32 v84, v86, v78
	v_mul_f32_e32 v88, v212, v85
	v_mul_f32_e32 v89, v213, v85
	v_mul_f32_e32 v85, v86, v79
	v_exp_f32_e32 v85, v85
	v_mul_f32_e32 v79, v87, v71
	v_exp_f32_e32 v79, v79
	v_exp_f32_e32 v84, v84
	v_fma_f32 v78, v85, v88, v88
	v_rcp_f32_e32 v85, v78
	v_mul_f32_e32 v78, v87, v70
	v_exp_f32_e32 v78, v78
	v_fma_f32 v70, v79, v89, v89
	v_rcp_f32_e32 v79, v70
	v_fma_f32 v84, v84, v88, v88
	v_fma_f32 v78, v78, v89, v89
	v_rcp_f32_e32 v78, v78
	v_rcp_f32_e32 v84, v84
	v_mad_i64_i32 v[82:83], s[28:29], v188, s23, v[130:131]
	v_pk_mul_f32 v[70:71], v[66:67], v[78:79]
	v_cvt_f32_i32_e32 v67, v81
	v_cvt_f32_i32_e32 v66, v80
	v_pk_mul_f32 v[74:75], v[74:75], v[84:85]
	v_mul_f32_e32 v79, v86, v67
	v_mul_f32_e32 v78, v86, v66
	v_exp_f32_e32 v78, v78
	v_exp_f32_e32 v79, v79
	v_pk_mul_f32 v[66:67], v[76:77], v[66:67]
	v_fma_f32 v78, v78, v88, v88
	v_fmac_f32_e32 v88, v79, v88
	v_rcp_f32_e32 v78, v78
	v_rcp_f32_e32 v79, v88
	s_nop 0
	v_pk_mul_f32 v[76:77], v[66:67], v[78:79]
	v_cvt_f32_i32_e32 v67, v73
	v_cvt_f32_i32_e32 v66, v72
	v_lshl_add_u64 v[78:79], v[82:83], 0, v[114:115]
	v_mul_f32_e32 v73, v87, v67
	v_mul_f32_e32 v72, v87, v66
	v_exp_f32_e32 v72, v72
	v_exp_f32_e32 v73, v73
	v_pk_mul_f32 v[66:67], v[68:69], v[66:67]
	v_cvt_pk_bf16_f32 v68, v70, v71
	v_fma_f32 v72, v72, v89, v89
	v_fmac_f32_e32 v89, v73, v89
	v_rcp_f32_e32 v72, v72
	v_rcp_f32_e32 v73, v89
	s_nop 0
	v_pk_mul_f32 v[72:73], v[66:67], v[72:73]
	v_cvt_pk_bf16_f32 v66, v74, v75
	v_cvt_pk_bf16_f32 v67, v76, v77
	v_cvt_pk_bf16_f32 v69, v72, v73
	global_store_dwordx4 v[78:79], v[66:69], off
	s_nop 1
	v_mul_f32_e32 v68, v216, v137
	v_mul_f32_e32 v69, v68, v68
	v_rcp_f32_e32 v69, v69
	v_mul_f32_e32 v70, v116, v68
	v_mul_f32_e32 v71, v132, v68
	v_mul_f32_e32 v68, v70, v62
	v_mul_f32_e32 v72, v212, v69
	v_mul_f32_e32 v73, v213, v69
	v_mul_f32_e32 v69, v70, v63
	v_exp_f32_e32 v69, v69
	v_mul_f32_e32 v63, v71, v55
	v_exp_f32_e32 v63, v63
	v_exp_f32_e32 v68, v68
	v_fma_f32 v62, v69, v72, v72
	v_rcp_f32_e32 v69, v62
	v_mul_f32_e32 v62, v71, v54
	v_exp_f32_e32 v62, v62
	v_fma_f32 v54, v63, v73, v73
	v_rcp_f32_e32 v63, v54
	v_fma_f32 v68, v68, v72, v72
	v_fma_f32 v62, v62, v73, v73
	v_rcp_f32_e32 v62, v62
	v_rcp_f32_e32 v68, v68
	v_mad_i64_i32 v[66:67], s[28:29], v186, s23, v[130:131]
	v_pk_mul_f32 v[54:55], v[50:51], v[62:63]
	v_cvt_f32_i32_e32 v51, v65
	v_cvt_f32_i32_e32 v50, v64
	v_pk_mul_f32 v[58:59], v[58:59], v[68:69]
	v_mul_f32_e32 v63, v70, v51
	v_mul_f32_e32 v62, v70, v50
	v_exp_f32_e32 v62, v62
	v_exp_f32_e32 v63, v63
	v_pk_mul_f32 v[50:51], v[60:61], v[50:51]
	v_fma_f32 v62, v62, v72, v72
	v_fmac_f32_e32 v72, v63, v72
	v_rcp_f32_e32 v62, v62
	v_rcp_f32_e32 v63, v72
	s_nop 0
	v_pk_mul_f32 v[60:61], v[50:51], v[62:63]
	v_cvt_f32_i32_e32 v51, v57
	v_cvt_f32_i32_e32 v50, v56
	v_lshl_add_u64 v[62:63], v[66:67], 0, v[114:115]
	v_mul_f32_e32 v57, v71, v51
	v_mul_f32_e32 v56, v71, v50
	v_exp_f32_e32 v56, v56
	v_exp_f32_e32 v57, v57
	v_pk_mul_f32 v[50:51], v[52:53], v[50:51]
	v_cvt_pk_bf16_f32 v52, v54, v55
	v_fma_f32 v56, v56, v73, v73
	v_fmac_f32_e32 v73, v57, v73
	v_rcp_f32_e32 v56, v56
	v_rcp_f32_e32 v57, v73
	s_nop 0
	v_pk_mul_f32 v[56:57], v[50:51], v[56:57]
	v_cvt_pk_bf16_f32 v50, v58, v59
	v_cvt_pk_bf16_f32 v51, v60, v61
	v_cvt_pk_bf16_f32 v53, v56, v57
	global_store_dwordx4 v[62:63], v[50:53], off
	s_nop 1
	v_mul_f32_e32 v52, v215, v136
	v_mul_f32_e32 v53, v52, v52
	v_rcp_f32_e32 v53, v53
	v_mul_f32_e32 v54, v116, v52
	v_mul_f32_e32 v55, v132, v52
	v_mul_f32_e32 v52, v54, v46
	v_mul_f32_e32 v56, v212, v53
	v_mul_f32_e32 v57, v213, v53
	v_mul_f32_e32 v53, v54, v47
	v_exp_f32_e32 v53, v53
	v_mul_f32_e32 v47, v55, v39
	v_exp_f32_e32 v47, v47
	v_exp_f32_e32 v52, v52
	v_fma_f32 v46, v53, v56, v56
	v_rcp_f32_e32 v53, v46
	v_mul_f32_e32 v46, v55, v38
	v_exp_f32_e32 v46, v46
	v_fma_f32 v38, v47, v57, v57
	v_rcp_f32_e32 v47, v38
	v_fma_f32 v52, v52, v56, v56
	v_fma_f32 v46, v46, v57, v57
	v_rcp_f32_e32 v46, v46
	v_rcp_f32_e32 v52, v52
	v_mad_i64_i32 v[50:51], s[28:29], v184, s23, v[130:131]
	v_pk_mul_f32 v[38:39], v[34:35], v[46:47]
	v_cvt_f32_i32_e32 v35, v49
	v_cvt_f32_i32_e32 v34, v48
	v_pk_mul_f32 v[42:43], v[42:43], v[52:53]
	v_mul_f32_e32 v47, v54, v35
	v_mul_f32_e32 v46, v54, v34
	v_exp_f32_e32 v46, v46
	v_exp_f32_e32 v47, v47
	v_pk_mul_f32 v[34:35], v[44:45], v[34:35]
	v_fma_f32 v46, v46, v56, v56
	v_fmac_f32_e32 v56, v47, v56
	v_rcp_f32_e32 v46, v46
	v_rcp_f32_e32 v47, v56
	s_nop 0
	v_pk_mul_f32 v[44:45], v[34:35], v[46:47]
	v_cvt_f32_i32_e32 v35, v41
	v_cvt_f32_i32_e32 v34, v40
	v_lshl_add_u64 v[46:47], v[50:51], 0, v[114:115]
	v_mul_f32_e32 v41, v55, v35
	v_mul_f32_e32 v40, v55, v34
	v_exp_f32_e32 v40, v40
	v_exp_f32_e32 v41, v41
	v_pk_mul_f32 v[34:35], v[36:37], v[34:35]
	v_cvt_pk_bf16_f32 v36, v38, v39
	v_fma_f32 v40, v40, v57, v57
	v_fmac_f32_e32 v57, v41, v57
	v_rcp_f32_e32 v40, v40
	v_rcp_f32_e32 v41, v57
	s_nop 0
	v_pk_mul_f32 v[40:41], v[34:35], v[40:41]
	v_cvt_pk_bf16_f32 v34, v42, v43
	v_cvt_pk_bf16_f32 v35, v44, v45
	v_cvt_pk_bf16_f32 v37, v40, v41
	global_store_dwordx4 v[46:47], v[34:37], off
	s_nop 1
	v_mul_f32_e32 v36, v214, v135
	v_mul_f32_e32 v37, v36, v36
	v_rcp_f32_e32 v37, v37
	v_mul_f32_e32 v38, v116, v36
	v_mul_f32_e32 v39, v132, v36
	v_mul_f32_e32 v36, v38, v30
	v_mul_f32_e32 v40, v212, v37
	v_mul_f32_e32 v41, v213, v37
	v_mul_f32_e32 v37, v38, v31
	v_exp_f32_e32 v37, v37
	v_mul_f32_e32 v31, v39, v23
	v_exp_f32_e32 v31, v31
	v_exp_f32_e32 v36, v36
	v_fma_f32 v30, v37, v40, v40
	v_rcp_f32_e32 v37, v30
	v_mul_f32_e32 v30, v39, v22
	v_exp_f32_e32 v30, v30
	v_fma_f32 v22, v31, v41, v41
	v_rcp_f32_e32 v31, v22
	v_fma_f32 v36, v36, v40, v40
	v_fma_f32 v30, v30, v41, v41
	v_rcp_f32_e32 v30, v30
	v_rcp_f32_e32 v36, v36
	v_mad_i64_i32 v[34:35], s[28:29], v182, s23, v[130:131]
	v_pk_mul_f32 v[22:23], v[18:19], v[30:31]
	v_cvt_f32_i32_e32 v19, v33
	v_cvt_f32_i32_e32 v18, v32
	v_pk_mul_f32 v[26:27], v[26:27], v[36:37]
	v_mul_f32_e32 v31, v38, v19
	v_mul_f32_e32 v30, v38, v18
	v_exp_f32_e32 v30, v30
	v_exp_f32_e32 v31, v31
	v_pk_mul_f32 v[18:19], v[28:29], v[18:19]
	v_fma_f32 v30, v30, v40, v40
	v_fmac_f32_e32 v40, v31, v40
	v_rcp_f32_e32 v30, v30
	v_rcp_f32_e32 v31, v40
	s_nop 0
	v_pk_mul_f32 v[28:29], v[18:19], v[30:31]
	v_cvt_f32_i32_e32 v19, v25
	v_cvt_f32_i32_e32 v18, v24
	v_lshl_add_u64 v[30:31], v[34:35], 0, v[114:115]
	v_mul_f32_e32 v25, v39, v19
	v_mul_f32_e32 v24, v39, v18
	v_exp_f32_e32 v24, v24
	v_exp_f32_e32 v25, v25
	v_pk_mul_f32 v[18:19], v[20:21], v[18:19]
	v_cvt_pk_bf16_f32 v20, v22, v23
	v_fma_f32 v24, v24, v41, v41
	v_fmac_f32_e32 v41, v25, v41
	v_rcp_f32_e32 v24, v24
	v_rcp_f32_e32 v25, v41
	s_nop 0
	v_pk_mul_f32 v[24:25], v[18:19], v[24:25]
	v_cvt_pk_bf16_f32 v18, v26, v27
	v_cvt_pk_bf16_f32 v19, v28, v29
	v_cvt_pk_bf16_f32 v21, v24, v25
	global_store_dwordx4 v[30:31], v[18:21], off
	s_nop 1
	v_mul_f32_e32 v20, v211, v134
	v_mul_f32_e32 v21, v20, v20
	v_rcp_f32_e32 v21, v21
	v_mul_f32_e32 v22, v116, v20
	v_mul_f32_e32 v23, v132, v20
	v_mul_f32_e32 v20, v22, v14
	v_mul_f32_e32 v24, v212, v21
	v_mul_f32_e32 v25, v213, v21
	v_mul_f32_e32 v21, v22, v15
	v_exp_f32_e32 v21, v21
	v_mul_f32_e32 v15, v23, v7
	v_exp_f32_e32 v15, v15
	v_exp_f32_e32 v20, v20
	v_fma_f32 v14, v21, v24, v24
	v_rcp_f32_e32 v21, v14
	v_mul_f32_e32 v14, v23, v6
	v_exp_f32_e32 v14, v14
	v_fma_f32 v6, v15, v25, v25
	v_rcp_f32_e32 v15, v6
	v_fma_f32 v20, v20, v24, v24
	v_fma_f32 v14, v14, v25, v25
	v_rcp_f32_e32 v14, v14
	v_rcp_f32_e32 v20, v20
	v_mad_i64_i32 v[18:19], s[28:29], v180, s23, v[130:131]
	v_pk_mul_f32 v[6:7], v[2:3], v[14:15]
	v_cvt_f32_i32_e32 v3, v17
	v_cvt_f32_i32_e32 v2, v16
	v_pk_mul_f32 v[10:11], v[10:11], v[20:21]
	v_mul_f32_e32 v15, v22, v3
	v_mul_f32_e32 v14, v22, v2
	v_exp_f32_e32 v14, v14
	v_exp_f32_e32 v15, v15
	v_pk_mul_f32 v[2:3], v[12:13], v[2:3]
	v_fma_f32 v14, v14, v24, v24
	v_fmac_f32_e32 v24, v15, v24
	v_rcp_f32_e32 v14, v14
	v_rcp_f32_e32 v15, v24
	s_nop 0
	v_pk_mul_f32 v[12:13], v[2:3], v[14:15]
	v_cvt_f32_i32_e32 v3, v9
	v_cvt_f32_i32_e32 v2, v8
	v_lshl_add_u64 v[14:15], v[18:19], 0, v[114:115]
	v_mul_f32_e32 v9, v23, v3
	v_mul_f32_e32 v8, v23, v2
	v_exp_f32_e32 v8, v8
	v_exp_f32_e32 v9, v9
	v_pk_mul_f32 v[2:3], v[4:5], v[2:3]
	v_cvt_pk_bf16_f32 v4, v6, v7
	v_fma_f32 v8, v8, v25, v25
	v_fmac_f32_e32 v25, v9, v25
	v_rcp_f32_e32 v8, v8
	v_rcp_f32_e32 v9, v25
	s_nop 0
	v_pk_mul_f32 v[8:9], v[2:3], v[8:9]
	v_cvt_pk_bf16_f32 v2, v10, v11
	v_cvt_pk_bf16_f32 v3, v12, v13
	v_cvt_pk_bf16_f32 v5, v8, v9
	global_store_dwordx4 v[14:15], v[2:5], off
	s_waitcnt vmcnt(4)
	s_cbranch_vccnz .LBB0_1210
	s_andn2_b64 vcc, exec, s[4:5]
	s_cbranch_vccnz .LBB0_1209
	s_barrier
	s_branch .LBB0_1209
